# v24 + double-buffered (2 batches in flight) S5 carry-in loop
# baseline (speedup 1.0000x reference)
; #define TIDX tid_()
; DEVI void s5_pass_b(const Params& p, int l, int witem, unsigned char* wlraw) {
;     unsigned char* ws = p.ws;
;     const int lane = TIDX & 63, l16 = lane & 15, quad = lane >> 4;
;     const int G = witem & 15, k = (witem >> 4) & 127, b = witem >> 11;
;     const int sidx = (l * 16 + G) * 64 + lane;
;     const float4 a4 = ((const float4*)(ws + OFF_S5A))[sidx];
;     bf16x8 bfr[8];
;     s5_bfrags(p, l, G, bfr);
;     float* us = (float*)wlraw;
;     bf16_t* Hs = (bf16_t*)(wlraw + 4096);
;     const int tok0 = b * S_ + k * 64;
;     s5_load_u((const float*)(ws + OFF_USSM), tok0, G, us, lane);
;     float hr = 0.f, hi = 0.f;
;     {
;         const float2* E = (const float2*)(ws + OFF_E) + ((size_t)(b * 128) * 16 + G) * 64 + lane;
; #pragma unroll 8
;         for (int kk = 0; kk < k; ++kk) {
;             const float2 e = E[(size_t)kk * 16 * 64];
.LBB0_706:
	v_mov_b32_e32 v0, v133
	s_lshl_b32 s24, s38, 2
	v_readfirstlane_b32 s22, v0
	s_ashr_i32 s22, s22, 6
	s_add_i32 s24, s22, s24
	s_xor_b32 s25, s24, 0x7f0
	s_cmpk_gt_i32 s38, 0x1ff
	s_cselect_b32 s42, s25, s24
	v_mov_b32_e32 v77, v133
	s_and_b32 s41, s42, 15
	s_barrier
	s_or_b32 s24, s41, s4
	v_and_b32_e32 v76, 63, v77
	v_lshl_or_b32 v2, s24, 6, v76
	v_ashrrev_i32_e32 v3, 31, v2
	s_ashr_i32 s25, s24, 31
	s_lshl_b32 s39, s22, 14
	s_bfe_u32 s43, s42, 0x70004
	s_ashr_i32 s26, s42, 11
	v_lshl_add_u64 v[2:3], v[2:3], 4, s[0:1]
	v_mov_b32_e32 v78, v133
	s_lshl_b64 s[46:47], s[24:25], 13
	global_load_dwordx4 v[2:5], v[2:3], off
	s_add_u32 s46, s6, s46
	v_lshlrev_b32_e32 v0, 7, v78
	s_addc_u32 s47, s10, s47
	v_and_b32_e32 v0, 0x780, v0
	v_lshl_add_u64 v[6:7], s[46:47], 0, v[0:1]
	v_lshlrev_b32_e32 v0, 1, v78
	v_and_b32_e32 v0, 32, v0
	v_lshl_add_u64 v[6:7], v[6:7], 0, v[0:1]
	s_movk_i32 s22, 0x1000
	v_add_co_u32_e32 v32, vcc, s22, v6
	s_lshl_b32 s22, s26, 13
	s_lshl_b32 s27, s43, 6
	s_mov_b64 s[44:45], 0x1000
	s_or_b32 s40, s27, s22
	v_lshl_add_u64 v[12:13], v[6:7], 0, s[44:45]
	v_addc_co_u32_e32 v33, vcc, 0, v7, vcc
	v_or_b32_e32 v50, s40, v76
	global_load_dwordx4 v[52:55], v[6:7], off offset:16
	global_load_dwordx4 v[60:63], v[6:7], off
	global_load_dwordx4 v[8:11], v[6:7], off offset:2064
	global_load_dwordx4 v[16:19], v[6:7], off offset:2048
	global_load_dwordx4 v[44:47], v[32:33], off
	s_nop 0
	global_load_dwordx4 v[12:15], v[12:13], off offset:16
	s_mov_b64 s[44:45], 0x1800
	global_load_dwordx4 v[20:23], v[6:7], off offset:80
	global_load_dwordx4 v[40:43], v[6:7], off offset:64
	global_load_dwordx4 v[24:27], v[6:7], off offset:2128
	global_load_dwordx4 v[36:39], v[6:7], off offset:2112
	v_ashrrev_i32_e32 v51, 31, v50
	v_lshl_add_u64 v[34:35], v[6:7], 0, s[44:45]
	v_lshlrev_b64 v[50:51], 10, v[50:51]
	s_mov_b64 s[44:45], 0x1040
	global_load_dwordx4 v[56:59], v[32:33], off offset:2048
	global_load_dwordx4 v[28:31], v[32:33], off offset:64
	global_load_dwordx4 v[64:67], v[34:35], off offset:16
	s_nop 0
	global_load_dwordx4 v[32:35], v[32:33], off offset:2112
	v_lshl_add_u64 v[50:51], s[14:15], 0, v[50:51]
	s_lshl_b32 s22, s41, 6
	v_lshl_add_u64 v[48:49], v[6:7], 0, s[44:45]
	s_mov_b64 s[44:45], 0x1840
	v_lshl_add_u64 v[50:51], v[50:51], 0, s[22:23]
	v_lshl_add_u64 v[6:7], v[6:7], 0, s[44:45]
	global_load_dwordx4 v[72:75], v[50:51], off offset:16
	global_load_dwordx4 v[80:83], v[50:51], off
	global_load_dwordx4 v[84:87], v[50:51], off offset:48
	global_load_dwordx4 v[88:91], v[50:51], off offset:32
	global_load_dwordx4 v[68:71], v[48:49], off offset:16
	s_nop 0
	global_load_dwordx4 v[48:51], v[6:7], off offset:16
	v_lshl_or_b32 v0, v76, 6, s39
	s_cmp_eq_u32 s43, 0
	s_waitcnt vmcnt(4)
	ds_write_b128 v0, v[80:83]
	ds_write_b128 v0, v[72:75] offset:16
	s_waitcnt vmcnt(2)
	ds_write_b128 v0, v[88:91] offset:32
	ds_write_b128 v0, v[84:87] offset:48
	s_cbranch_scc1 .LBB0_711
	s_lshl_b32 s26, s26, 7
	s_ashr_i32 s27, s26, 31
	s_lshl_b64 s[26:27], s[26:27], 13
	s_cmp_lt_u32 s43, 8
	v_lshlrev_b32_e32 v0, 3, v76
	s_cbranch_scc1 .LBB0_712
	s_lshr_b32 s22, s42, 4
	s_and_b32 s22, s22, 0x78
	s_lshl_b32 s43, s41, 9
	s_add_u32 s43, s26, s43
	s_addc_u32 s47, s27, 0
	s_add_u32 s46, s17, s43
	s_addc_u32 s47, s28, s47
	v_mov_b32_e32 v72, 0
	v_pk_mov_b32 v[6:7], v[4:5], v[4:5] op_sel:[1,0]
	v_lshl_add_u64 v[74:75], s[46:47], 0, v[0:1]
	s_mov_b32 s43, 0
	v_mov_b32_e32 v73, v72
	v_add_co_u32_e32 v82, vcc, 0xffff2000, v74
	s_nop 1
	v_addc_co_u32_e32 v83, vcc, -1, v75, vcc
	global_load_dwordx2 v[92:93], v[82:83], off
	v_add_co_u32_e32 v82, vcc, 0xffff4000, v74
	s_nop 1
	v_addc_co_u32_e32 v83, vcc, -1, v75, vcc
	global_load_dwordx2 v[94:95], v[82:83], off
	v_add_co_u32_e32 v82, vcc, 0xffff6000, v74
	s_nop 1
	v_addc_co_u32_e32 v83, vcc, -1, v75, vcc
	global_load_dwordx2 v[96:97], v[82:83], off
	v_add_co_u32_e32 v82, vcc, 0xffff8000, v74
	s_nop 1
	v_addc_co_u32_e32 v83, vcc, -1, v75, vcc
	global_load_dwordx2 v[98:99], v[82:83], off
	v_add_co_u32_e32 v82, vcc, 0xffffa000, v74
	s_nop 1
	v_addc_co_u32_e32 v83, vcc, -1, v75, vcc
	global_load_dwordx2 v[100:101], v[82:83], off
	v_add_co_u32_e32 v82, vcc, 0xffffc000, v74
	s_nop 1
	v_addc_co_u32_e32 v83, vcc, -1, v75, vcc
	global_load_dwordx2 v[102:103], v[82:83], off
	v_add_co_u32_e32 v82, vcc, 0xffffe000, v74
	s_nop 1
	v_addc_co_u32_e32 v83, vcc, -1, v75, vcc
	global_load_dwordx2 v[104:105], v[82:83], off
	global_load_dwordx2 v[106:107], v[74:75], off
	s_mov_b64 s[46:47], 0x10000
	v_lshl_add_u64 v[74:75], v[74:75], 0, s[46:47]
; DEVI void s5_pass_b(const Params& p, int l, int witem, unsigned char* wlraw) {
;     ...
;     {
;         const float2* E = (const float2*)(ws + OFF_E) + ((size_t)(b * 128) * 16 + G) * 64 + lane;
; #pragma unroll 8
;         for (int kk = 0; kk < k; ++kk) {
;             const float2 e = E[(size_t)kk * 16 * 64];
;             const float nr = a4.z * hr - a4.w * hi + e.x, ni = a4.z * hi + a4.w * hr + e.y;
;             hr = nr; hi = ni;
;         }
.LBB0_709:
	s_add_i32 s43, s43, 8
	s_cmp_eq_u32 s22, s43
	s_cbranch_scc1 .Lcar_A_last
	v_add_co_u32_e32 v82, vcc, 0xffff2000, v74
	s_nop 1
	v_addc_co_u32_e32 v83, vcc, -1, v75, vcc
	global_load_dwordx2 v[108:109], v[82:83], off
	v_add_co_u32_e32 v82, vcc, 0xffff4000, v74
	s_nop 1
	v_addc_co_u32_e32 v83, vcc, -1, v75, vcc
	global_load_dwordx2 v[110:111], v[82:83], off
	v_add_co_u32_e32 v82, vcc, 0xffff6000, v74
	s_nop 1
	v_addc_co_u32_e32 v83, vcc, -1, v75, vcc
	global_load_dwordx2 v[112:113], v[82:83], off
	v_add_co_u32_e32 v82, vcc, 0xffff8000, v74
	s_nop 1
	v_addc_co_u32_e32 v83, vcc, -1, v75, vcc
	global_load_dwordx2 v[114:115], v[82:83], off
	v_add_co_u32_e32 v82, vcc, 0xffffa000, v74
	s_nop 1
	v_addc_co_u32_e32 v83, vcc, -1, v75, vcc
	global_load_dwordx2 v[116:117], v[82:83], off
	v_add_co_u32_e32 v82, vcc, 0xffffc000, v74
	s_nop 1
	v_addc_co_u32_e32 v83, vcc, -1, v75, vcc
	global_load_dwordx2 v[118:119], v[82:83], off
	v_add_co_u32_e32 v82, vcc, 0xffffe000, v74
	s_nop 1
	v_addc_co_u32_e32 v83, vcc, -1, v75, vcc
	global_load_dwordx2 v[120:121], v[82:83], off
	global_load_dwordx2 v[122:123], v[74:75], off
	s_mov_b64 s[46:47], 0x10000
	v_lshl_add_u64 v[74:75], v[74:75], 0, s[46:47]
	v_mov_b32_e32 v80, v73
	v_pk_mul_f32 v[80:81], v[6:7], v[80:81] op_sel_hi:[1,0]
	s_nop 0
	v_pk_fma_f32 v[84:85], v[4:5], v[72:73], v[80:81] neg_lo:[0,0,1] neg_hi:[0,0,1]
	v_pk_fma_f32 v[72:73], v[4:5], v[72:73], v[80:81] op_sel_hi:[1,0,1]
	s_nop 0
	v_mov_b32_e32 v85, v73
	s_waitcnt vmcnt(15)
	v_pk_add_f32 v[72:73], v[84:85], v[92:93]
	s_nop 0
	v_pk_mul_f32 v[80:81], v[6:7], v[72:73] op_sel:[0,1]
	s_nop 0
	v_pk_fma_f32 v[84:85], v[4:5], v[72:73], v[80:81] neg_lo:[0,0,1] neg_hi:[0,0,1]
	v_pk_fma_f32 v[72:73], v[4:5], v[72:73], v[80:81] op_sel_hi:[1,0,1]
	s_nop 0
	v_mov_b32_e32 v85, v73
	s_waitcnt vmcnt(14)
	v_pk_add_f32 v[72:73], v[84:85], v[94:95]
	s_nop 0
	v_pk_mul_f32 v[80:81], v[6:7], v[72:73] op_sel:[0,1]
	s_nop 0
	v_pk_fma_f32 v[84:85], v[4:5], v[72:73], v[80:81] neg_lo:[0,0,1] neg_hi:[0,0,1]
	v_pk_fma_f32 v[72:73], v[4:5], v[72:73], v[80:81] op_sel_hi:[1,0,1]
	s_nop 0
	v_mov_b32_e32 v85, v73
	s_waitcnt vmcnt(13)
	v_pk_add_f32 v[72:73], v[84:85], v[96:97]
	s_nop 0
	v_pk_mul_f32 v[80:81], v[6:7], v[72:73] op_sel:[0,1]
	s_nop 0
	v_pk_fma_f32 v[84:85], v[4:5], v[72:73], v[80:81] neg_lo:[0,0,1] neg_hi:[0,0,1]
	v_pk_fma_f32 v[72:73], v[4:5], v[72:73], v[80:81] op_sel_hi:[1,0,1]
	s_nop 0
	v_mov_b32_e32 v85, v73
	s_waitcnt vmcnt(12)
	v_pk_add_f32 v[72:73], v[84:85], v[98:99]
	s_nop 0
	v_pk_mul_f32 v[80:81], v[6:7], v[72:73] op_sel:[0,1]
	s_nop 0
	v_pk_fma_f32 v[84:85], v[4:5], v[72:73], v[80:81] neg_lo:[0,0,1] neg_hi:[0,0,1]
	v_pk_fma_f32 v[72:73], v[4:5], v[72:73], v[80:81] op_sel_hi:[1,0,1]
	s_nop 0
	v_mov_b32_e32 v85, v73
	s_waitcnt vmcnt(11)
	v_pk_add_f32 v[72:73], v[84:85], v[100:101]
	s_nop 0
	v_pk_mul_f32 v[80:81], v[6:7], v[72:73] op_sel:[0,1]
	s_nop 0
	v_pk_fma_f32 v[84:85], v[4:5], v[72:73], v[80:81] neg_lo:[0,0,1] neg_hi:[0,0,1]
	v_pk_fma_f32 v[72:73], v[4:5], v[72:73], v[80:81] op_sel_hi:[1,0,1]
	s_nop 0
	v_mov_b32_e32 v85, v73
	s_waitcnt vmcnt(10)
	v_pk_add_f32 v[72:73], v[84:85], v[102:103]
	s_nop 0
	v_pk_mul_f32 v[80:81], v[6:7], v[72:73] op_sel:[0,1]
	s_nop 0
	v_pk_fma_f32 v[84:85], v[4:5], v[72:73], v[80:81] neg_lo:[0,0,1] neg_hi:[0,0,1]
	v_pk_fma_f32 v[72:73], v[4:5], v[72:73], v[80:81] op_sel_hi:[1,0,1]
	s_nop 0
	v_mov_b32_e32 v85, v73
	s_waitcnt vmcnt(9)
	v_pk_add_f32 v[72:73], v[84:85], v[104:105]
	s_nop 0
	v_pk_mul_f32 v[80:81], v[6:7], v[72:73] op_sel:[0,1]
	s_nop 0
	v_pk_fma_f32 v[84:85], v[4:5], v[72:73], v[80:81] neg_lo:[0,0,1] neg_hi:[0,0,1]
	v_pk_fma_f32 v[72:73], v[4:5], v[72:73], v[80:81] op_sel_hi:[1,0,1]
	s_nop 0
	v_mov_b32_e32 v85, v73
	s_waitcnt vmcnt(8)
	v_pk_add_f32 v[72:73], v[84:85], v[106:107]
	s_add_i32 s43, s43, 8
	s_cmp_eq_u32 s22, s43
	s_cbranch_scc1 .Lcar_B_last
	v_add_co_u32_e32 v82, vcc, 0xffff2000, v74
	s_nop 1
	v_addc_co_u32_e32 v83, vcc, -1, v75, vcc
	global_load_dwordx2 v[92:93], v[82:83], off
	v_add_co_u32_e32 v82, vcc, 0xffff4000, v74
	s_nop 1
	v_addc_co_u32_e32 v83, vcc, -1, v75, vcc
	global_load_dwordx2 v[94:95], v[82:83], off
	v_add_co_u32_e32 v82, vcc, 0xffff6000, v74
	s_nop 1
	v_addc_co_u32_e32 v83, vcc, -1, v75, vcc
	global_load_dwordx2 v[96:97], v[82:83], off
	v_add_co_u32_e32 v82, vcc, 0xffff8000, v74
	s_nop 1
	v_addc_co_u32_e32 v83, vcc, -1, v75, vcc
	global_load_dwordx2 v[98:99], v[82:83], off
	v_add_co_u32_e32 v82, vcc, 0xffffa000, v74
	s_nop 1
	v_addc_co_u32_e32 v83, vcc, -1, v75, vcc
	global_load_dwordx2 v[100:101], v[82:83], off
	v_add_co_u32_e32 v82, vcc, 0xffffc000, v74
	s_nop 1
	v_addc_co_u32_e32 v83, vcc, -1, v75, vcc
	global_load_dwordx2 v[102:103], v[82:83], off
	v_add_co_u32_e32 v82, vcc, 0xffffe000, v74
	s_nop 1
	v_addc_co_u32_e32 v83, vcc, -1, v75, vcc
	global_load_dwordx2 v[104:105], v[82:83], off
	global_load_dwordx2 v[106:107], v[74:75], off
	s_mov_b64 s[46:47], 0x10000
	v_lshl_add_u64 v[74:75], v[74:75], 0, s[46:47]
	v_mov_b32_e32 v80, v73
	v_pk_mul_f32 v[80:81], v[6:7], v[80:81] op_sel_hi:[1,0]
	s_nop 0
	v_pk_fma_f32 v[84:85], v[4:5], v[72:73], v[80:81] neg_lo:[0,0,1] neg_hi:[0,0,1]
	v_pk_fma_f32 v[72:73], v[4:5], v[72:73], v[80:81] op_sel_hi:[1,0,1]
	s_nop 0
	v_mov_b32_e32 v85, v73
	s_waitcnt vmcnt(15)
	v_pk_add_f32 v[72:73], v[84:85], v[108:109]
	s_nop 0
	v_pk_mul_f32 v[80:81], v[6:7], v[72:73] op_sel:[0,1]
	s_nop 0
	v_pk_fma_f32 v[84:85], v[4:5], v[72:73], v[80:81] neg_lo:[0,0,1] neg_hi:[0,0,1]
	v_pk_fma_f32 v[72:73], v[4:5], v[72:73], v[80:81] op_sel_hi:[1,0,1]
	s_nop 0
	v_mov_b32_e32 v85, v73
	s_waitcnt vmcnt(14)
; DEVI void s5_pass_b(const Params& p, int l, int witem, unsigned char* wlraw) {
;     ...
;     {
;         const float2* E = (const float2*)(ws + OFF_E) + ((size_t)(b * 128) * 16 + G) * 64 + lane;
; #pragma unroll 8
;         for (int kk = 0; kk < k; ++kk) {
;             const float2 e = E[(size_t)kk * 16 * 64];
;             const float nr = a4.z * hr - a4.w * hi + e.x, ni = a4.z * hi + a4.w * hr + e.y;
;             hr = nr; hi = ni;
;         }
	v_pk_add_f32 v[72:73], v[84:85], v[110:111]
	s_nop 0
	v_pk_mul_f32 v[80:81], v[6:7], v[72:73] op_sel:[0,1]
	s_nop 0
	v_pk_fma_f32 v[84:85], v[4:5], v[72:73], v[80:81] neg_lo:[0,0,1] neg_hi:[0,0,1]
	v_pk_fma_f32 v[72:73], v[4:5], v[72:73], v[80:81] op_sel_hi:[1,0,1]
	s_nop 0
	v_mov_b32_e32 v85, v73
	s_waitcnt vmcnt(13)
	v_pk_add_f32 v[72:73], v[84:85], v[112:113]
	s_nop 0
	v_pk_mul_f32 v[80:81], v[6:7], v[72:73] op_sel:[0,1]
	s_nop 0
	v_pk_fma_f32 v[84:85], v[4:5], v[72:73], v[80:81] neg_lo:[0,0,1] neg_hi:[0,0,1]
	v_pk_fma_f32 v[72:73], v[4:5], v[72:73], v[80:81] op_sel_hi:[1,0,1]
	s_nop 0
	v_mov_b32_e32 v85, v73
	s_waitcnt vmcnt(12)
	v_pk_add_f32 v[72:73], v[84:85], v[114:115]
	s_nop 0
	v_pk_mul_f32 v[80:81], v[6:7], v[72:73] op_sel:[0,1]
	s_nop 0
	v_pk_fma_f32 v[84:85], v[4:5], v[72:73], v[80:81] neg_lo:[0,0,1] neg_hi:[0,0,1]
	v_pk_fma_f32 v[72:73], v[4:5], v[72:73], v[80:81] op_sel_hi:[1,0,1]
	s_nop 0
	v_mov_b32_e32 v85, v73
	s_waitcnt vmcnt(11)
	v_pk_add_f32 v[72:73], v[84:85], v[116:117]
	s_nop 0
	v_pk_mul_f32 v[80:81], v[6:7], v[72:73] op_sel:[0,1]
	s_nop 0
	v_pk_fma_f32 v[84:85], v[4:5], v[72:73], v[80:81] neg_lo:[0,0,1] neg_hi:[0,0,1]
	v_pk_fma_f32 v[72:73], v[4:5], v[72:73], v[80:81] op_sel_hi:[1,0,1]
	s_nop 0
	v_mov_b32_e32 v85, v73
	s_waitcnt vmcnt(10)
	v_pk_add_f32 v[72:73], v[84:85], v[118:119]
	s_nop 0
	v_pk_mul_f32 v[80:81], v[6:7], v[72:73] op_sel:[0,1]
	s_nop 0
	v_pk_fma_f32 v[84:85], v[4:5], v[72:73], v[80:81] neg_lo:[0,0,1] neg_hi:[0,0,1]
	v_pk_fma_f32 v[72:73], v[4:5], v[72:73], v[80:81] op_sel_hi:[1,0,1]
	s_nop 0
	v_mov_b32_e32 v85, v73
	s_waitcnt vmcnt(9)
	v_pk_add_f32 v[72:73], v[84:85], v[120:121]
	s_nop 0
	v_pk_mul_f32 v[80:81], v[6:7], v[72:73] op_sel:[0,1]
	s_nop 0
	v_pk_fma_f32 v[84:85], v[4:5], v[72:73], v[80:81] neg_lo:[0,0,1] neg_hi:[0,0,1]
	v_pk_fma_f32 v[72:73], v[4:5], v[72:73], v[80:81] op_sel_hi:[1,0,1]
	s_nop 0
	v_mov_b32_e32 v85, v73
	s_waitcnt vmcnt(8)
	v_pk_add_f32 v[72:73], v[84:85], v[122:123]
	s_branch .LBB0_709
.Lcar_A_last:
	v_mov_b32_e32 v80, v73
	v_pk_mul_f32 v[80:81], v[6:7], v[80:81] op_sel_hi:[1,0]
	s_nop 0
	v_pk_fma_f32 v[84:85], v[4:5], v[72:73], v[80:81] neg_lo:[0,0,1] neg_hi:[0,0,1]
	v_pk_fma_f32 v[72:73], v[4:5], v[72:73], v[80:81] op_sel_hi:[1,0,1]
	s_nop 0
	v_mov_b32_e32 v85, v73
	s_waitcnt vmcnt(7)
	v_pk_add_f32 v[72:73], v[84:85], v[92:93]
	s_nop 0
	v_pk_mul_f32 v[80:81], v[6:7], v[72:73] op_sel:[0,1]
	s_nop 0
	v_pk_fma_f32 v[84:85], v[4:5], v[72:73], v[80:81] neg_lo:[0,0,1] neg_hi:[0,0,1]
	v_pk_fma_f32 v[72:73], v[4:5], v[72:73], v[80:81] op_sel_hi:[1,0,1]
	s_nop 0
	v_mov_b32_e32 v85, v73
	s_waitcnt vmcnt(6)
	v_pk_add_f32 v[72:73], v[84:85], v[94:95]
	s_nop 0
	v_pk_mul_f32 v[80:81], v[6:7], v[72:73] op_sel:[0,1]
	s_nop 0
	v_pk_fma_f32 v[84:85], v[4:5], v[72:73], v[80:81] neg_lo:[0,0,1] neg_hi:[0,0,1]
	v_pk_fma_f32 v[72:73], v[4:5], v[72:73], v[80:81] op_sel_hi:[1,0,1]
	s_nop 0
	v_mov_b32_e32 v85, v73
	s_waitcnt vmcnt(5)
	v_pk_add_f32 v[72:73], v[84:85], v[96:97]
	s_nop 0
	v_pk_mul_f32 v[80:81], v[6:7], v[72:73] op_sel:[0,1]
	s_nop 0
	v_pk_fma_f32 v[84:85], v[4:5], v[72:73], v[80:81] neg_lo:[0,0,1] neg_hi:[0,0,1]
	v_pk_fma_f32 v[72:73], v[4:5], v[72:73], v[80:81] op_sel_hi:[1,0,1]
	s_nop 0
	v_mov_b32_e32 v85, v73
	s_waitcnt vmcnt(4)
	v_pk_add_f32 v[72:73], v[84:85], v[98:99]
	s_nop 0
	v_pk_mul_f32 v[80:81], v[6:7], v[72:73] op_sel:[0,1]
	s_nop 0
	v_pk_fma_f32 v[84:85], v[4:5], v[72:73], v[80:81] neg_lo:[0,0,1] neg_hi:[0,0,1]
	v_pk_fma_f32 v[72:73], v[4:5], v[72:73], v[80:81] op_sel_hi:[1,0,1]
	s_nop 0
	v_mov_b32_e32 v85, v73
	s_waitcnt vmcnt(3)
	v_pk_add_f32 v[72:73], v[84:85], v[100:101]
	s_nop 0
	v_pk_mul_f32 v[80:81], v[6:7], v[72:73] op_sel:[0,1]
	s_nop 0
	v_pk_fma_f32 v[84:85], v[4:5], v[72:73], v[80:81] neg_lo:[0,0,1] neg_hi:[0,0,1]
	v_pk_fma_f32 v[72:73], v[4:5], v[72:73], v[80:81] op_sel_hi:[1,0,1]
	s_nop 0
	v_mov_b32_e32 v85, v73
	s_waitcnt vmcnt(2)
	v_pk_add_f32 v[72:73], v[84:85], v[102:103]
	s_nop 0
	v_pk_mul_f32 v[80:81], v[6:7], v[72:73] op_sel:[0,1]
	s_nop 0
	v_pk_fma_f32 v[84:85], v[4:5], v[72:73], v[80:81] neg_lo:[0,0,1] neg_hi:[0,0,1]
	v_pk_fma_f32 v[72:73], v[4:5], v[72:73], v[80:81] op_sel_hi:[1,0,1]
	s_nop 0
	v_mov_b32_e32 v85, v73
	s_waitcnt vmcnt(1)
	v_pk_add_f32 v[72:73], v[84:85], v[104:105]
	s_nop 0
	v_pk_mul_f32 v[80:81], v[6:7], v[72:73] op_sel:[0,1]
	s_nop 0
	v_pk_fma_f32 v[84:85], v[4:5], v[72:73], v[80:81] neg_lo:[0,0,1] neg_hi:[0,0,1]
	v_pk_fma_f32 v[72:73], v[4:5], v[72:73], v[80:81] op_sel_hi:[1,0,1]
	s_nop 0
	v_mov_b32_e32 v85, v73
	s_waitcnt vmcnt(0)
	v_pk_add_f32 v[72:73], v[84:85], v[106:107]
	s_branch .Lcar_done
; DEVI void s5_pass_b(const Params& p, int l, int witem, unsigned char* wlraw) {
;     ...
;     {
;         const float2* E = (const float2*)(ws + OFF_E) + ((size_t)(b * 128) * 16 + G) * 64 + lane;
; #pragma unroll 8
;         for (int kk = 0; kk < k; ++kk) {
;             const float2 e = E[(size_t)kk * 16 * 64];
;             const float nr = a4.z * hr - a4.w * hi + e.x, ni = a4.z * hi + a4.w * hr + e.y;
;             hr = nr; hi = ni;
;         }
;     }
.Lcar_B_last:
	v_mov_b32_e32 v80, v73
	v_pk_mul_f32 v[80:81], v[6:7], v[80:81] op_sel_hi:[1,0]
	s_nop 0
	v_pk_fma_f32 v[84:85], v[4:5], v[72:73], v[80:81] neg_lo:[0,0,1] neg_hi:[0,0,1]
	v_pk_fma_f32 v[72:73], v[4:5], v[72:73], v[80:81] op_sel_hi:[1,0,1]
	s_nop 0
	v_mov_b32_e32 v85, v73
	s_waitcnt vmcnt(7)
	v_pk_add_f32 v[72:73], v[84:85], v[108:109]
	s_nop 0
	v_pk_mul_f32 v[80:81], v[6:7], v[72:73] op_sel:[0,1]
	s_nop 0
	v_pk_fma_f32 v[84:85], v[4:5], v[72:73], v[80:81] neg_lo:[0,0,1] neg_hi:[0,0,1]
	v_pk_fma_f32 v[72:73], v[4:5], v[72:73], v[80:81] op_sel_hi:[1,0,1]
	s_nop 0
	v_mov_b32_e32 v85, v73
	s_waitcnt vmcnt(6)
	v_pk_add_f32 v[72:73], v[84:85], v[110:111]
	s_nop 0
	v_pk_mul_f32 v[80:81], v[6:7], v[72:73] op_sel:[0,1]
	s_nop 0
	v_pk_fma_f32 v[84:85], v[4:5], v[72:73], v[80:81] neg_lo:[0,0,1] neg_hi:[0,0,1]
	v_pk_fma_f32 v[72:73], v[4:5], v[72:73], v[80:81] op_sel_hi:[1,0,1]
	s_nop 0
	v_mov_b32_e32 v85, v73
	s_waitcnt vmcnt(5)
	v_pk_add_f32 v[72:73], v[84:85], v[112:113]
	s_nop 0
	v_pk_mul_f32 v[80:81], v[6:7], v[72:73] op_sel:[0,1]
	s_nop 0
	v_pk_fma_f32 v[84:85], v[4:5], v[72:73], v[80:81] neg_lo:[0,0,1] neg_hi:[0,0,1]
	v_pk_fma_f32 v[72:73], v[4:5], v[72:73], v[80:81] op_sel_hi:[1,0,1]
	s_nop 0
	v_mov_b32_e32 v85, v73
	s_waitcnt vmcnt(4)
	v_pk_add_f32 v[72:73], v[84:85], v[114:115]
	s_nop 0
	v_pk_mul_f32 v[80:81], v[6:7], v[72:73] op_sel:[0,1]
	s_nop 0
	v_pk_fma_f32 v[84:85], v[4:5], v[72:73], v[80:81] neg_lo:[0,0,1] neg_hi:[0,0,1]
	v_pk_fma_f32 v[72:73], v[4:5], v[72:73], v[80:81] op_sel_hi:[1,0,1]
	s_nop 0
	v_mov_b32_e32 v85, v73
	s_waitcnt vmcnt(3)
	v_pk_add_f32 v[72:73], v[84:85], v[116:117]
	s_nop 0
	v_pk_mul_f32 v[80:81], v[6:7], v[72:73] op_sel:[0,1]
	s_nop 0
	v_pk_fma_f32 v[84:85], v[4:5], v[72:73], v[80:81] neg_lo:[0,0,1] neg_hi:[0,0,1]
	v_pk_fma_f32 v[72:73], v[4:5], v[72:73], v[80:81] op_sel_hi:[1,0,1]
	s_nop 0
	v_mov_b32_e32 v85, v73
	s_waitcnt vmcnt(2)
	v_pk_add_f32 v[72:73], v[84:85], v[118:119]
	s_nop 0
	v_pk_mul_f32 v[80:81], v[6:7], v[72:73] op_sel:[0,1]
	s_nop 0
	v_pk_fma_f32 v[84:85], v[4:5], v[72:73], v[80:81] neg_lo:[0,0,1] neg_hi:[0,0,1]
	v_pk_fma_f32 v[72:73], v[4:5], v[72:73], v[80:81] op_sel_hi:[1,0,1]
	s_nop 0
	v_mov_b32_e32 v85, v73
	s_waitcnt vmcnt(1)
	v_pk_add_f32 v[72:73], v[84:85], v[120:121]
	s_nop 0
	v_pk_mul_f32 v[80:81], v[6:7], v[72:73] op_sel:[0,1]
	s_nop 0
	v_pk_fma_f32 v[84:85], v[4:5], v[72:73], v[80:81] neg_lo:[0,0,1] neg_hi:[0,0,1]
	v_pk_fma_f32 v[72:73], v[4:5], v[72:73], v[80:81] op_sel_hi:[1,0,1]
	s_nop 0
	v_mov_b32_e32 v85, v73
	s_waitcnt vmcnt(0)
	v_pk_add_f32 v[72:73], v[84:85], v[122:123]
.Lcar_done:
	s_bfe_u32 s42, s42, 0x30004
	s_cmp_eq_u32 s42, 0
	s_cbranch_scc0 .LBB0_713
	s_branch .LBB0_715
